# SSD decode item: lane reductions via DPP/permlane swap instead of ds_bpermute
# baseline (speedup 1.0000x reference)
; DI float bf2f(u16 b) { return __uint_as_float(((unsigned)b) << 16); }
; DI float silu_f(float x) { return x * __builtin_amdgcn_rcpf(1.f + __expf(-x)); }
; DI float softplus_f(float x) { return x > 20.f ? x : log1pf(__expf(x)); }
; PH void ssd_decode_item(const Params& p, int layer, int b, int e) {
;     ...
;   const float dtv = softplus_f(bf2f(PROJ[row * NPAD + C_DT + e]) + p.in[20][layer * 12 + e]);
;   const float dA = __expf(dtv * (-__expf(p.in[21][layer * 12 + e])));
;   const float Dv = p.in[22][layer * 12 + e];
;   if (tid < 64) xs_s[tid] = bf2f(xsr);
;   if (tid < 128) { Bv[tid] = bf2f(bvr); Cv[tid] = bf2f(cvr); }
;   __syncthreads();
;   const float4 Bq = *(const float4*)(Bv + n4 * 4), Cq = *(const float4*)(Cv + n4 * 4);
; #pragma unroll
;   for (int i = 0; i < 8; ++i) {
;     const int pidx = (tid >> 5) + 8 * i;
;     const float xsv = xs_s[pidx];
;     const float xdt = dtv * xsv;
;     f32x4 hn;
;     hn[0] = dA * hv[i][0] + xdt * Bq.x; hn[1] = dA * hv[i][1] + xdt * Bq.y; hn[2] = dA * hv[i][2] + xdt * Bq.z; hn[3] = dA * hv[i][3] + xdt * Bq.w;
;     *(f32x4*)(h1 + (size_t)pidx * 128 + n4 * 4) = hn;
;     float part = Cq.x * hn[0] + Cq.y * hn[1] + Cq.z * hn[2] + Cq.w * hn[3];
; #pragma unroll
;     for (int d = 1; d < 32; d <<= 1) part += __shfl_xor(part, d);
;     if (n4 == 0) ys[pidx] = (part + Dv * xsv) * silu_f(bf2f(zv[i]));
.LBB0_379:
	v_readlane_b32 s36, v252, 37
	v_readlane_b32 s46, v252, 47
	v_readlane_b32 s47, v252, 48
	s_add_u32 s6, s46, s0
	v_readlane_b32 s48, v252, 49
	s_addc_u32 s7, s47, s1
	v_readlane_b32 s49, v252, 50
	s_add_u32 s0, s48, s0
	s_addc_u32 s1, s49, s1
	global_load_dword v32, v161, s[6:7]
	global_load_dword v68, v161, s[0:1]
	v_cmp_gt_i32_e32 vcc, 64, v40
	v_lshl_add_u32 v66, v40, 2, 32
	v_readlane_b32 s37, v252, 38
	v_readlane_b32 s38, v252, 39
	v_readlane_b32 s39, v252, 40
	v_readlane_b32 s40, v252, 41
	v_readlane_b32 s41, v252, 42
	v_readlane_b32 s42, v252, 43
	v_readlane_b32 s43, v252, 44
	v_readlane_b32 s44, v252, 45
	v_readlane_b32 s45, v252, 46
	v_readlane_b32 s50, v252, 51
	v_readlane_b32 s51, v252, 52
	s_and_saveexec_b64 s[0:1], vcc
	v_lshlrev_b32_e32 v31, 16, v31
	ds_write_b32 v66, v31
	s_or_b64 exec, exec, s[0:1]
	s_movk_i32 s0, 0x80
	v_cmp_gt_i32_e64 s[0:1], s0, v40
	s_and_saveexec_b64 s[6:7], s[0:1]
	v_lshlrev_b32_e32 v29, 16, v29
	v_lshlrev_b32_e32 v30, 16, v30
	ds_write2st64_b32 v66, v29, v30 offset0:1 offset1:3
	s_or_b64 exec, exec, s[6:7]
	s_waitcnt vmcnt(1)
	v_mul_f32_e32 v29, 0x3fb8aa3b, v32
	v_exp_f32_e32 v29, v29
	v_lshlrev_b32_e32 v30, 2, v57
	v_lshlrev_b32_e32 v160, 2, v30
	v_add_u32_e32 v30, 32, v160
	s_waitcnt lgkmcnt(0)
	s_barrier
	v_lshl_add_u32 v73, v28, 2, 32
	ds_read_b128 v[32:35], v30 offset:256
	ds_read_b32 v75, v73
	v_mul_f32_e64 v29, v67, -v29
	v_mul_f32_e32 v29, 0x3fb8aa3b, v29
	v_exp_f32_e32 v56, v29
	ds_read_b128 v[28:31], v30 offset:768
	s_waitcnt lgkmcnt(1)
	v_mul_f32_e32 v70, v67, v75
	v_pk_mul_f32 v[76:77], v[32:33], v[70:71] op_sel_hi:[1,0]
	v_and_b32_e32 v64, 64, v190
	v_pk_fma_f32 v[78:79], v[36:37], v[56:57], v[76:77] op_sel_hi:[1,0,1]
	v_pk_mul_f32 v[36:37], v[34:35], v[70:71] op_sel_hi:[1,0]
	v_add_u32_e32 v64, 64, v64
	v_pk_fma_f32 v[80:81], v[38:39], v[56:57], v[36:37] op_sel_hi:[1,0,1]
	s_waitcnt lgkmcnt(0)
	v_mul_f32_e32 v36, v29, v79
	v_xor_b32_e32 v37, 1, v190
	v_fmac_f32_e32 v36, v28, v78
	v_cmp_lt_i32_e64 s[0:1], v37, v64
	v_fmac_f32_e32 v36, v30, v80
	v_fmac_f32_e32 v36, v31, v81
	v_cndmask_b32_e64 v37, v190, v37, s[0:1]
	v_lshlrev_b32_e32 v39, 2, v37
	s_nop 1
	v_mov_b32_dpp v37, v36 quad_perm:[1,0,3,2] row_mask:0xf bank_mask:0xf
	v_cmp_eq_u32_e64 s[36:37], 0, v57
	s_waitcnt lgkmcnt(0)
	v_add_f32_e32 v36, v36, v37
	v_xor_b32_e32 v37, 2, v190
	v_cmp_lt_i32_e64 s[0:1], v37, v64
	s_nop 1
	v_cndmask_b32_e64 v37, v190, v37, s[0:1]
	v_lshlrev_b32_e32 v69, 2, v37
	s_nop 1
	v_mov_b32_dpp v37, v36 quad_perm:[2,3,0,1] row_mask:0xf bank_mask:0xf
	s_waitcnt lgkmcnt(0)
	v_add_f32_e32 v36, v36, v37
	v_xor_b32_e32 v37, 4, v190
	v_cmp_lt_i32_e64 s[0:1], v37, v64
	s_nop 1
	v_cndmask_b32_e64 v37, v190, v37, s[0:1]
	v_lshlrev_b32_e32 v70, 2, v37
	s_nop 1
	v_mov_b32_dpp v37, v36 row_half_mirror row_mask:0xf bank_mask:0xf
	s_waitcnt lgkmcnt(0)
	v_add_f32_e32 v36, v36, v37
	v_xor_b32_e32 v37, 8, v190
	v_cmp_lt_i32_e64 s[0:1], v37, v64
	s_nop 1
	v_cndmask_b32_e64 v37, v190, v37, s[0:1]
	v_lshlrev_b32_e32 v38, 2, v37
	s_nop 1
	v_mov_b32_dpp v37, v36 row_mirror row_mask:0xf bank_mask:0xf
	v_readlane_b32 s0, v254, 20
	s_add_u32 s6, s0, s8
	v_readlane_b32 s0, v254, 21
	s_addc_u32 s7, s0, s9
	s_waitcnt lgkmcnt(0)
	v_add_f32_e32 v76, v36, v37
	v_xor_b32_e32 v36, 16, v190
	v_cmp_lt_i32_e64 s[0:1], v36, v64
	s_nop 1
	v_cndmask_b32_e64 v36, v190, v36, s[0:1]
	v_lshlrev_b32_e32 v71, 2, v36
	v_mov_b32_e32 v77, v76
	s_nop 1
	v_permlane16_swap_b32_e32 v76, v77
	v_lshl_add_u64 v[36:37], s[6:7], 0, v[160:161]
	v_lshl_add_u64 v[58:59], v[36:37], 0, v[58:59]
	global_store_dwordx4 v[58:59], v[78:81], off
	s_and_saveexec_b64 s[0:1], s[36:37]
	s_cbranch_execz .LBB0_385
	v_lshlrev_b32_e32 v57, 16, v74
	v_mul_f32_e32 v58, 0xbfb8aa3b, v57
	v_exp_f32_e32 v58, v58
	s_waitcnt lgkmcnt(0)
	v_add_f32_e32 v59, v76, v77
	s_waitcnt vmcnt(1)
	v_fmac_f32_e32 v59, v68, v75
	v_add_f32_e32 v58, 1.0, v58
	v_rcp_f32_e32 v58, v58
	s_nop 0
	v_mul_f32_e32 v57, v58, v57
	v_mul_f32_e32 v57, v57, v59
	ds_write_b32 v73, v57 offset:1280
.LBB0_385:
	s_or_b64 exec, exec, s[0:1]
	ds_read_b32 v58, v73 offset:32
	v_mov_b32_e32 v57, v56
	v_lshl_add_u64 v[54:55], v[36:37], 0, v[54:55]
	s_waitcnt lgkmcnt(0)
	v_mul_f32_e32 v74, v67, v58
	v_pk_mul_f32 v[76:77], v[32:33], v[74:75] op_sel_hi:[1,0]
	v_pk_mul_f32 v[74:75], v[34:35], v[74:75] op_sel_hi:[1,0]
	v_pk_fma_f32 v[24:25], v[24:25], v[56:57], v[76:77]
	v_pk_fma_f32 v[26:27], v[26:27], v[56:57], v[74:75]
	global_store_dwordx4 v[54:55], v[24:27], off
	s_nop 1
	v_mul_f32_e32 v25, v29, v25
	v_fmac_f32_e32 v25, v28, v24
	v_fmac_f32_e32 v25, v30, v26
	v_fmac_f32_e32 v25, v31, v27
	s_nop 1
	v_mov_b32_dpp v24, v25 quad_perm:[1,0,3,2] row_mask:0xf bank_mask:0xf
	s_waitcnt lgkmcnt(0)
	v_add_f32_e32 v24, v25, v24
	s_nop 1
	v_mov_b32_dpp v25, v24 quad_perm:[2,3,0,1] row_mask:0xf bank_mask:0xf
	s_waitcnt lgkmcnt(0)
	v_add_f32_e32 v24, v24, v25
	s_nop 1
	v_mov_b32_dpp v25, v24 row_half_mirror row_mask:0xf bank_mask:0xf
	s_waitcnt lgkmcnt(0)
	v_add_f32_e32 v24, v24, v25
	s_nop 1
	v_mov_b32_dpp v25, v24 row_mirror row_mask:0xf bank_mask:0xf
	s_waitcnt lgkmcnt(0)
	v_add_f32_e32 v24, v24, v25
	v_mov_b32_e32 v25, v24
	s_nop 1
	v_permlane16_swap_b32_e32 v24, v25
	s_and_saveexec_b64 s[0:1], s[36:37]
	s_cbranch_execz .LBB0_387
	v_lshlrev_b32_e32 v26, 16, v72
	v_mul_f32_e32 v27, 0xbfb8aa3b, v26
	v_exp_f32_e32 v27, v27
	s_waitcnt lgkmcnt(0)
	v_add_f32_e32 v24, v24, v25
	s_waitcnt vmcnt(2)
	v_fmac_f32_e32 v24, v68, v58
	v_add_f32_e32 v27, 1.0, v27
	v_rcp_f32_e32 v27, v27
	s_nop 0
	v_mul_f32_e32 v25, v27, v26
	v_mul_f32_e32 v24, v25, v24
	ds_write_b32 v73, v24 offset:1312
; DI float bf2f(u16 b) { return __uint_as_float(((unsigned)b) << 16); }
; DI float silu_f(float x) { return x * __builtin_amdgcn_rcpf(1.f + __expf(-x)); }
; PH void ssd_decode_item(const Params& p, int layer, int b, int e) {
;     ...
; #pragma unroll
;   for (int i = 0; i < 8; ++i) {
;     const int pidx = (tid >> 5) + 8 * i;
;     const float xsv = xs_s[pidx];
;     const float xdt = dtv * xsv;
;     f32x4 hn;
;     hn[0] = dA * hv[i][0] + xdt * Bq.x; hn[1] = dA * hv[i][1] + xdt * Bq.y; hn[2] = dA * hv[i][2] + xdt * Bq.z; hn[3] = dA * hv[i][3] + xdt * Bq.w;
;     *(f32x4*)(h1 + (size_t)pidx * 128 + n4 * 4) = hn;
;     float part = Cq.x * hn[0] + Cq.y * hn[1] + Cq.z * hn[2] + Cq.w * hn[3];
; #pragma unroll
;     for (int d = 1; d < 32; d <<= 1) part += __shfl_xor(part, d);
;     if (n4 == 0) ys[pidx] = (part + Dv * xsv) * silu_f(bf2f(zv[i]));
;   }
.LBB0_387:
	s_or_b64 exec, exec, s[0:1]
	ds_read_b32 v24, v73 offset:64
	s_waitcnt lgkmcnt(0)
	v_mul_f32_e32 v26, v67, v24
	v_pk_mul_f32 v[54:55], v[32:33], v[26:27] op_sel_hi:[1,0]
	v_pk_mul_f32 v[26:27], v[34:35], v[26:27] op_sel_hi:[1,0]
	v_pk_fma_f32 v[20:21], v[20:21], v[56:57], v[54:55]
	v_pk_fma_f32 v[22:23], v[22:23], v[56:57], v[26:27]
	v_lshl_add_u64 v[26:27], v[36:37], 0, v[52:53]
	global_store_dwordx4 v[26:27], v[20:23], off
	s_nop 1
	v_mul_f32_e32 v21, v29, v21
	v_fmac_f32_e32 v21, v28, v20
	v_fmac_f32_e32 v21, v30, v22
	v_fmac_f32_e32 v21, v31, v23
	s_nop 1
	v_mov_b32_dpp v20, v21 quad_perm:[1,0,3,2] row_mask:0xf bank_mask:0xf
	s_waitcnt lgkmcnt(0)
	v_add_f32_e32 v20, v21, v20
	s_nop 1
	v_mov_b32_dpp v21, v20 quad_perm:[2,3,0,1] row_mask:0xf bank_mask:0xf
	s_waitcnt lgkmcnt(0)
	v_add_f32_e32 v20, v20, v21
	s_nop 1
	v_mov_b32_dpp v21, v20 row_half_mirror row_mask:0xf bank_mask:0xf
	s_waitcnt lgkmcnt(0)
	v_add_f32_e32 v20, v20, v21
	s_nop 1
	v_mov_b32_dpp v21, v20 row_mirror row_mask:0xf bank_mask:0xf
	s_waitcnt lgkmcnt(0)
	v_add_f32_e32 v20, v20, v21
	v_mov_b32_e32 v21, v20
	s_nop 1
	v_permlane16_swap_b32_e32 v20, v21
	s_and_saveexec_b64 s[0:1], s[36:37]
	s_cbranch_execz .LBB0_389
	v_lshlrev_b32_e32 v22, 16, v65
	v_mul_f32_e32 v23, 0xbfb8aa3b, v22
	v_exp_f32_e32 v23, v23
	s_waitcnt lgkmcnt(0)
	v_add_f32_e32 v20, v20, v21
	s_waitcnt vmcnt(3)
	v_fmac_f32_e32 v20, v68, v24
	v_add_f32_e32 v23, 1.0, v23
	v_rcp_f32_e32 v23, v23
	s_nop 0
	v_mul_f32_e32 v21, v23, v22
	v_mul_f32_e32 v20, v21, v20
	ds_write_b32 v73, v20 offset:1344
.LBB0_389:
	s_or_b64 exec, exec, s[0:1]
	ds_read_b32 v20, v73 offset:96
	s_waitcnt lgkmcnt(0)
	v_mul_f32_e32 v22, v67, v20
	v_pk_mul_f32 v[24:25], v[32:33], v[22:23] op_sel_hi:[1,0]
	v_pk_mul_f32 v[22:23], v[34:35], v[22:23] op_sel_hi:[1,0]
	v_pk_fma_f32 v[16:17], v[16:17], v[56:57], v[24:25]
	v_pk_fma_f32 v[18:19], v[18:19], v[56:57], v[22:23]
	v_lshl_add_u64 v[22:23], v[36:37], 0, v[50:51]
	global_store_dwordx4 v[22:23], v[16:19], off
	s_nop 1
	v_mul_f32_e32 v17, v29, v17
	v_fmac_f32_e32 v17, v28, v16
	v_fmac_f32_e32 v17, v30, v18
	v_fmac_f32_e32 v17, v31, v19
	s_nop 1
	v_mov_b32_dpp v16, v17 quad_perm:[1,0,3,2] row_mask:0xf bank_mask:0xf
	s_waitcnt lgkmcnt(0)
	v_add_f32_e32 v16, v17, v16
	s_nop 1
	v_mov_b32_dpp v17, v16 quad_perm:[2,3,0,1] row_mask:0xf bank_mask:0xf
	s_waitcnt lgkmcnt(0)
	v_add_f32_e32 v16, v16, v17
	s_nop 1
	v_mov_b32_dpp v17, v16 row_half_mirror row_mask:0xf bank_mask:0xf
	s_waitcnt lgkmcnt(0)
	v_add_f32_e32 v16, v16, v17
	s_nop 1
	v_mov_b32_dpp v17, v16 row_mirror row_mask:0xf bank_mask:0xf
	s_waitcnt lgkmcnt(0)
	v_add_f32_e32 v16, v16, v17
	v_mov_b32_e32 v17, v16
	s_nop 1
	v_permlane16_swap_b32_e32 v16, v17
	s_and_saveexec_b64 s[0:1], s[36:37]
	s_cbranch_execz .LBB0_391
	v_lshlrev_b32_e32 v18, 16, v63
	v_mul_f32_e32 v19, 0xbfb8aa3b, v18
	v_exp_f32_e32 v19, v19
	s_waitcnt lgkmcnt(0)
	v_add_f32_e32 v16, v16, v17
	s_waitcnt vmcnt(4)
	v_fmac_f32_e32 v16, v68, v20
	v_add_f32_e32 v19, 1.0, v19
	v_rcp_f32_e32 v19, v19
	s_nop 0
	v_mul_f32_e32 v17, v19, v18
	v_mul_f32_e32 v16, v17, v16
	ds_write_b32 v73, v16 offset:1376
.LBB0_391:
	s_or_b64 exec, exec, s[0:1]
	ds_read_b32 v16, v73 offset:128
	s_waitcnt lgkmcnt(0)
	v_mul_f32_e32 v18, v67, v16
	v_pk_mul_f32 v[20:21], v[32:33], v[18:19] op_sel_hi:[1,0]
	v_pk_mul_f32 v[18:19], v[34:35], v[18:19] op_sel_hi:[1,0]
	v_pk_fma_f32 v[12:13], v[12:13], v[56:57], v[20:21]
	v_pk_fma_f32 v[14:15], v[14:15], v[56:57], v[18:19]
	v_lshl_add_u64 v[18:19], v[36:37], 0, v[48:49]
	global_store_dwordx4 v[18:19], v[12:15], off
	s_nop 1
	v_mul_f32_e32 v13, v29, v13
	v_fmac_f32_e32 v13, v28, v12
	v_fmac_f32_e32 v13, v30, v14
	v_fmac_f32_e32 v13, v31, v15
	s_nop 1
	v_mov_b32_dpp v12, v13 quad_perm:[1,0,3,2] row_mask:0xf bank_mask:0xf
	s_waitcnt lgkmcnt(0)
	v_add_f32_e32 v12, v13, v12
	s_nop 1
	v_mov_b32_dpp v13, v12 quad_perm:[2,3,0,1] row_mask:0xf bank_mask:0xf
	s_waitcnt lgkmcnt(0)
	v_add_f32_e32 v12, v12, v13
	s_nop 1
	v_mov_b32_dpp v13, v12 row_half_mirror row_mask:0xf bank_mask:0xf
	s_waitcnt lgkmcnt(0)
	v_add_f32_e32 v12, v12, v13
	s_nop 1
	v_mov_b32_dpp v13, v12 row_mirror row_mask:0xf bank_mask:0xf
	s_waitcnt lgkmcnt(0)
	v_add_f32_e32 v12, v12, v13
	v_mov_b32_e32 v13, v12
	s_nop 1
	v_permlane16_swap_b32_e32 v12, v13
	s_and_saveexec_b64 s[0:1], s[36:37]
	s_cbranch_execz .LBB0_393
	v_lshlrev_b32_e32 v14, 16, v62
	v_mul_f32_e32 v15, 0xbfb8aa3b, v14
	v_exp_f32_e32 v15, v15
	s_waitcnt lgkmcnt(0)
	v_add_f32_e32 v12, v12, v13
	s_waitcnt vmcnt(5)
	v_fmac_f32_e32 v12, v68, v16
	v_add_f32_e32 v15, 1.0, v15
	v_rcp_f32_e32 v15, v15
	s_nop 0
	v_mul_f32_e32 v13, v15, v14
	v_mul_f32_e32 v12, v13, v12
	ds_write_b32 v73, v12 offset:1408
; DI float bf2f(u16 b) { return __uint_as_float(((unsigned)b) << 16); }
; DI float silu_f(float x) { return x * __builtin_amdgcn_rcpf(1.f + __expf(-x)); }
; PH void ssd_decode_item(const Params& p, int layer, int b, int e) {
;     ...
; #pragma unroll
;   for (int i = 0; i < 8; ++i) {
;     const int pidx = (tid >> 5) + 8 * i;
;     const float xsv = xs_s[pidx];
;     const float xdt = dtv * xsv;
;     f32x4 hn;
;     hn[0] = dA * hv[i][0] + xdt * Bq.x; hn[1] = dA * hv[i][1] + xdt * Bq.y; hn[2] = dA * hv[i][2] + xdt * Bq.z; hn[3] = dA * hv[i][3] + xdt * Bq.w;
;     *(f32x4*)(h1 + (size_t)pidx * 128 + n4 * 4) = hn;
;     float part = Cq.x * hn[0] + Cq.y * hn[1] + Cq.z * hn[2] + Cq.w * hn[3];
; #pragma unroll
;     for (int d = 1; d < 32; d <<= 1) part += __shfl_xor(part, d);
;     if (n4 == 0) ys[pidx] = (part + Dv * xsv) * silu_f(bf2f(zv[i]));
;   }
;   __syncthreads();
;   if (tid < 64) {
;     const float v = ys[tid];
;     MIX[row * 2048 + 1280 + e * 64 + tid] = f2bf(v);
;     float ss = v * v;
; #pragma unroll
;     for (int d = 1; d < 64; d <<= 1) ss += __shfl_xor(ss, d);
;     if (tid == 0) SSQ[row * 12 + e] = ss;
;   }
.LBB0_393:
	s_or_b64 exec, exec, s[0:1]
	ds_read_b32 v12, v73 offset:160
	s_waitcnt lgkmcnt(0)
	v_mul_f32_e32 v14, v67, v12
	v_pk_mul_f32 v[16:17], v[32:33], v[14:15] op_sel_hi:[1,0]
	v_pk_mul_f32 v[14:15], v[34:35], v[14:15] op_sel_hi:[1,0]
	v_pk_fma_f32 v[8:9], v[8:9], v[56:57], v[16:17]
	v_pk_fma_f32 v[10:11], v[10:11], v[56:57], v[14:15]
	v_lshl_add_u64 v[14:15], v[36:37], 0, v[46:47]
	global_store_dwordx4 v[14:15], v[8:11], off
	s_nop 1
	v_mul_f32_e32 v9, v29, v9
	v_fmac_f32_e32 v9, v28, v8
	v_fmac_f32_e32 v9, v30, v10
	v_fmac_f32_e32 v9, v31, v11
	s_nop 1
	v_mov_b32_dpp v8, v9 quad_perm:[1,0,3,2] row_mask:0xf bank_mask:0xf
	s_waitcnt lgkmcnt(0)
	v_add_f32_e32 v8, v9, v8
	s_nop 1
	v_mov_b32_dpp v9, v8 quad_perm:[2,3,0,1] row_mask:0xf bank_mask:0xf
	s_waitcnt lgkmcnt(0)
	v_add_f32_e32 v8, v8, v9
	s_nop 1
	v_mov_b32_dpp v9, v8 row_half_mirror row_mask:0xf bank_mask:0xf
	s_waitcnt lgkmcnt(0)
	v_add_f32_e32 v8, v8, v9
	s_nop 1
	v_mov_b32_dpp v9, v8 row_mirror row_mask:0xf bank_mask:0xf
	s_waitcnt lgkmcnt(0)
	v_add_f32_e32 v8, v8, v9
	v_mov_b32_e32 v9, v8
	s_nop 1
	v_permlane16_swap_b32_e32 v8, v9
	s_and_saveexec_b64 s[0:1], s[36:37]
	s_cbranch_execz .LBB0_395
	v_lshlrev_b32_e32 v10, 16, v61
	v_mul_f32_e32 v11, 0xbfb8aa3b, v10
	v_exp_f32_e32 v11, v11
	s_waitcnt lgkmcnt(0)
	v_add_f32_e32 v8, v8, v9
	s_waitcnt vmcnt(6)
	v_fmac_f32_e32 v8, v68, v12
	v_add_f32_e32 v11, 1.0, v11
	v_rcp_f32_e32 v11, v11
	s_nop 0
	v_mul_f32_e32 v9, v11, v10
	v_mul_f32_e32 v8, v9, v8
	ds_write_b32 v73, v8 offset:1440
.LBB0_395:
	s_or_b64 exec, exec, s[0:1]
	ds_read_b32 v8, v73 offset:192
	s_waitcnt lgkmcnt(0)
	v_mul_f32_e32 v10, v67, v8
	v_pk_mul_f32 v[12:13], v[32:33], v[10:11] op_sel_hi:[1,0]
	v_pk_mul_f32 v[10:11], v[34:35], v[10:11] op_sel_hi:[1,0]
	v_pk_fma_f32 v[4:5], v[4:5], v[56:57], v[12:13]
	v_pk_fma_f32 v[6:7], v[6:7], v[56:57], v[10:11]
	v_lshl_add_u64 v[10:11], v[36:37], 0, v[44:45]
	global_store_dwordx4 v[10:11], v[4:7], off
	s_nop 1
	v_mul_f32_e32 v5, v29, v5
	v_fmac_f32_e32 v5, v28, v4
	v_fmac_f32_e32 v5, v30, v6
	v_fmac_f32_e32 v5, v31, v7
	s_nop 1
	v_mov_b32_dpp v4, v5 quad_perm:[1,0,3,2] row_mask:0xf bank_mask:0xf
	s_waitcnt lgkmcnt(0)
	v_add_f32_e32 v4, v5, v4
	s_nop 1
	v_mov_b32_dpp v5, v4 quad_perm:[2,3,0,1] row_mask:0xf bank_mask:0xf
	s_waitcnt lgkmcnt(0)
	v_add_f32_e32 v4, v4, v5
	s_nop 1
	v_mov_b32_dpp v5, v4 row_half_mirror row_mask:0xf bank_mask:0xf
	s_waitcnt lgkmcnt(0)
	v_add_f32_e32 v4, v4, v5
	s_nop 1
	v_mov_b32_dpp v5, v4 row_mirror row_mask:0xf bank_mask:0xf
	s_waitcnt lgkmcnt(0)
	v_add_f32_e32 v4, v4, v5
	v_mov_b32_e32 v5, v4
	s_nop 1
	v_permlane16_swap_b32_e32 v4, v5
	s_and_saveexec_b64 s[0:1], s[36:37]
	s_cbranch_execz .LBB0_397
	v_lshlrev_b32_e32 v6, 16, v60
	v_mul_f32_e32 v7, 0xbfb8aa3b, v6
	v_exp_f32_e32 v7, v7
	s_waitcnt lgkmcnt(0)
	v_add_f32_e32 v4, v4, v5
	s_waitcnt vmcnt(7)
	v_fmac_f32_e32 v4, v68, v8
	v_add_f32_e32 v7, 1.0, v7
	v_rcp_f32_e32 v7, v7
	s_nop 0
	v_mul_f32_e32 v5, v7, v6
	v_mul_f32_e32 v4, v5, v4
	ds_write_b32 v73, v4 offset:1472
.LBB0_397:
	s_or_b64 exec, exec, s[0:1]
	ds_read_b32 v4, v73 offset:224
	s_waitcnt lgkmcnt(0)
	v_mul_f32_e32 v6, v67, v4
	v_pk_mul_f32 v[8:9], v[32:33], v[6:7] op_sel_hi:[1,0]
	v_pk_mul_f32 v[10:11], v[34:35], v[6:7] op_sel_hi:[1,0]
	v_pk_fma_f32 v[6:7], v[0:1], v[56:57], v[8:9]
	v_pk_fma_f32 v[8:9], v[2:3], v[56:57], v[10:11]
	v_mul_f32_e32 v0, v29, v7
	v_fmac_f32_e32 v0, v28, v6
	v_fmac_f32_e32 v0, v30, v8
	v_fmac_f32_e32 v0, v31, v9
	s_nop 1
	v_mov_b32_dpp v1, v0 quad_perm:[1,0,3,2] row_mask:0xf bank_mask:0xf
	v_lshl_add_u64 v[2:3], v[36:37], 0, v[42:43]
	global_store_dwordx4 v[2:3], v[6:9], off
	s_waitcnt lgkmcnt(0)
	v_add_f32_e32 v0, v0, v1
	s_nop 1
	v_mov_b32_dpp v1, v0 quad_perm:[2,3,0,1] row_mask:0xf bank_mask:0xf
	s_waitcnt lgkmcnt(0)
	v_add_f32_e32 v0, v0, v1
	s_nop 1
	v_mov_b32_dpp v1, v0 row_half_mirror row_mask:0xf bank_mask:0xf
	s_waitcnt lgkmcnt(0)
	v_add_f32_e32 v0, v0, v1
	s_nop 1
	v_mov_b32_dpp v1, v0 row_mirror row_mask:0xf bank_mask:0xf
	s_waitcnt lgkmcnt(0)
	v_add_f32_e32 v0, v0, v1
	v_mov_b32_e32 v1, v0
	s_nop 1
	v_permlane16_swap_b32_e32 v0, v1
	s_and_saveexec_b64 s[0:1], s[36:37]
	s_cbranch_execz .LBB0_399
	v_lshlrev_b32_e32 v2, 16, v41
	v_mul_f32_e32 v3, 0xbfb8aa3b, v2
	v_exp_f32_e32 v3, v3
	s_waitcnt lgkmcnt(0)
	v_add_f32_e32 v0, v0, v1
	s_waitcnt vmcnt(8)
	v_fmac_f32_e32 v0, v68, v4
	v_add_f32_e32 v3, 1.0, v3
	v_rcp_f32_e32 v3, v3
	s_nop 0
	v_mul_f32_e32 v1, v3, v2
	v_mul_f32_e32 v0, v1, v0
	ds_write_b32 v73, v0 offset:1504
.LBB0_399:
	s_or_b64 exec, exec, s[0:1]
	s_waitcnt lgkmcnt(0)
	s_barrier
	s_and_saveexec_b64 s[0:1], vcc
	s_cbranch_execz .LBB0_402
	s_lshl_b32 s2, s13, 6
	ds_read_b32 v2, v66 offset:1280
	s_lshl_b32 s6, s15, 12
	v_readlane_b32 s7, v254, 24
	s_add_u32 s6, s7, s6
	v_readlane_b32 s7, v254, 25
	s_addc_u32 s7, s7, 0
	s_lshl_b32 s2, s2, 1
	s_add_u32 s6, s6, s2
	v_ashrrev_i32_e32 v41, 31, v40
	s_addc_u32 s7, s7, 0
	s_waitcnt lgkmcnt(0)
	v_cvt_pk_bf16_f32 v3, v2, s0
	v_lshl_add_u64 v[0:1], v[40:41], 1, s[6:7]
	global_store_short v[0:1], v3, off
	v_mul_f32_e32 v0, v2, v2
	s_nop 1
	v_mov_b32_dpp v0, v0 quad_perm:[1,0,3,2] row_mask:0xf bank_mask:0xf
	s_waitcnt lgkmcnt(0)
	v_fmac_f32_e32 v0, v2, v2
	s_nop 1
	v_mov_b32_dpp v1, v0 quad_perm:[2,3,0,1] row_mask:0xf bank_mask:0xf
	s_waitcnt lgkmcnt(0)
	v_add_f32_e32 v0, v0, v1
	s_nop 1
	v_mov_b32_dpp v1, v0 row_half_mirror row_mask:0xf bank_mask:0xf
	s_waitcnt lgkmcnt(0)
	v_add_f32_e32 v0, v0, v1
	s_nop 1
	v_mov_b32_dpp v1, v0 row_mirror row_mask:0xf bank_mask:0xf
	s_waitcnt lgkmcnt(0)
	v_add_f32_e32 v0, v0, v1
	v_mov_b32_e32 v1, v0
	s_nop 1
	v_permlane16_swap_b32_e32 v0, v1
	s_waitcnt lgkmcnt(0)
	v_add_f32_e32 v0, v0, v1
	v_xor_b32_e32 v1, 32, v190
	v_cmp_lt_i32_e32 vcc, v1, v64
	s_nop 1
	v_cndmask_b32_e32 v1, v190, v1, vcc
	v_lshlrev_b32_e32 v1, 2, v1
	v_mov_b32_e32 v1, v0
	s_nop 1
	v_permlane32_swap_b32_e32 v0, v1
	v_cmp_eq_u32_e32 vcc, 0, v40
	s_and_b64 exec, exec, vcc
	s_cbranch_execz .LBB0_402
	s_mul_i32 s15, s15, 48
	v_readlane_b32 s6, v254, 22
	v_readlane_b32 s7, v254, 23
	s_add_u32 s6, s6, s15
	s_addc_u32 s7, s7, 0
	s_lshl_b32 s2, s13, 2
	s_waitcnt lgkmcnt(0)
	v_add_f32_e32 v0, v0, v1
	v_mov_b32_e32 v1, s2
	global_store_dword v1, v0, s[6:7]

; DI float softplus_f(float x) { return x > 20.f ? x : log1pf(__expf(x)); }
; PH void lru_item(const Params& p, int layer, int b, int n, int dpart) {
;     ...
;   const u16* WA = (const u16*)(p.ws + WS_WA) + (size_t)(layer * 8 + n) * 9216;
;   const u16* WX = (const u16*)(p.ws + WS_WX) + (size_t)(layer * 8 + n) * 9216;
;   bf16x8 wa[2][3], wx[2][3];
; #pragma unroll
;   for (int dt = 0; dt < 2; ++dt)
; #pragma unroll
;     for (int ks = 0; ks < 3; ++ks) {
;       const int d = dpart * 32 + dt * 16 + l15, k = ks * 32 + quad * 8;
;       wa[dt][ks] = *(const bf16x8*)(WA + d * 96 + k);
;       wx[dt][ks] = *(const bf16x8*)(WX + d * 96 + k);
;     }
;   const int nchunks = (b >= 0) ? 16 : 1;
;   const int sch = tid & 31, sub = tid >> 5;
;   const int chg = n * 96 + dpart * 32 + sch;
;   const float ba = p.in[14][layer * 768 + chg], bx = p.in[16][layer * 768 + chg];
;   const float cl = -8.f * softplus_f(-p.in[17][layer * 768 + chg]);
.LBB0_403:
	s_and_b64 vcc, exec, s[0:1]
	s_cbranch_vccz .LBB0_619
	s_nop 0
	s_nop 0
	s_nop 0
	s_nop 0
	s_nop 0
	s_nop 0
	s_nop 0
	s_nop 0
	s_nop 0
	s_nop 0
	s_nop 0
	s_nop 0
	s_nop 0
	s_nop 0
	s_nop 0
	s_nop 0
	s_nop 0
	s_nop 0
	s_nop 0
	s_nop 0
	s_nop 0
	s_nop 0
	s_nop 0
	s_nop 0
	s_nop 0
	s_nop 0
	s_nop 0
	s_nop 0
	s_nop 0
	s_nop 0
	s_nop 0
	s_nop 0
	s_add_i32 s0, s84, 0xffc0
	s_and_b32 s1, s0, 0xff
	s_mulk_i32 s1, 0xab
	s_bfe_u32 s8, s1, 0x70009
	s_mul_i32 s1, s8, 3
	s_sub_i32 s9, s0, s1
	v_readlane_b32 s0, v255, 46
	s_add_i32 s0, s0, s8
	s_mul_i32 s2, s0, 0x2400
	s_lshl_b64 s[0:1], s[2:3], 1
	v_readlane_b32 s2, v254, 28
	s_add_u32 s6, s2, s0
	v_readlane_b32 s2, v254, 29
	s_addc_u32 s7, s2, s1
	v_readlane_b32 s2, v254, 30
	s_add_u32 s0, s2, s0
	v_readlane_b32 s2, v254, 31
	v_mov_b32_e32 v77, v182
	s_addc_u32 s1, s2, s1
	s_lshl_b32 s2, s9, 5
	s_and_b32 s2, s2, 0xe0
	v_and_b32_e32 v78, 15, v77
	s_waitcnt vmcnt(6)
	v_or_b32_e32 v0, s2, v78
	v_mul_u32_u24_e32 v0, 0x60, v0
	v_bfe_u32 v73, v77, 4, 2
	v_lshlrev_b32_e32 v160, 1, v0
	s_waitcnt lgkmcnt(0)
	v_lshl_add_u64 v[0:1], s[6:7], 0, v[160:161]
	v_lshl_add_u64 v[2:3], s[0:1], 0, v[160:161]
	v_lshlrev_b32_e32 v160, 4, v73
	v_lshl_add_u64 v[0:1], v[0:1], 0, v[160:161]
	v_lshl_add_u64 v[2:3], v[2:3], 0, v[160:161]
	global_load_dwordx4 v[32:35], v[0:1], off
	global_load_dwordx4 v[24:27], v[0:1], off offset:64
	global_load_dwordx4 v[36:39], v[2:3], off
	global_load_dwordx4 v[16:19], v[2:3], off offset:64
	global_load_dwordx4 v[12:15], v[0:1], off offset:128
	global_load_dwordx4 v[40:43], v[0:1], off offset:3072
	global_load_dwordx4 v[8:11], v[2:3], off offset:128
	global_load_dwordx4 v[44:47], v[2:3], off offset:3072
	global_load_dwordx4 v[28:31], v[0:1], off offset:3136
	global_load_dwordx4 v[4:7], v[0:1], off offset:3200
	global_load_dwordx4 v[20:23], v[2:3], off offset:3136
	s_nop 0
	global_load_dwordx4 v[0:3], v[2:3], off offset:3200
	s_mul_i32 s6, s8, 0x60
	v_and_b32_e32 v76, 31, v77
	s_add_i32 s0, s6, s2
	v_or_b32_e32 v116, s0, v76
	v_readlane_b32 s0, v255, 41
	v_readlane_b32 s36, v252, 21
	v_readlane_b32 s37, v252, 22
	v_add_u32_e32 v160, s0, v116
	v_lshlrev_b64 v[50:51], 2, v[160:161]
	v_readlane_b32 s38, v252, 23
	v_readlane_b32 s39, v252, 24
	v_readlane_b32 s40, v252, 25
	v_readlane_b32 s41, v252, 26
	v_readlane_b32 s42, v252, 27
	v_readlane_b32 s43, v252, 28
	v_readlane_b32 s44, v252, 29
	v_readlane_b32 s45, v252, 30
	v_readlane_b32 s46, v252, 31
	v_readlane_b32 s47, v252, 32
	v_readlane_b32 s48, v252, 33
	v_readlane_b32 s49, v252, 34
	v_readlane_b32 s50, v252, 35
	v_readlane_b32 s51, v252, 36
	v_lshl_add_u64 v[48:49], s[48:49], 0, v[50:51]
	v_readlane_b32 s36, v252, 37
	v_readlane_b32 s38, v252, 39
	v_readlane_b32 s39, v252, 40
	global_load_dword v114, v[48:49], off
	v_readlane_b32 s37, v252, 38
	v_lshl_add_u64 v[48:49], s[38:39], 0, v[50:51]
	global_load_dword v48, v[48:49], off
	v_lshl_add_u64 v[50:51], s[36:37], 0, v[50:51]
	global_load_dword v115, v[50:51], off
	s_mov_b32 s0, 0xc1a00000
	v_readlane_b32 s1, v255, 42
	v_readlane_b32 s40, v252, 41
	v_readlane_b32 s41, v252, 42
	v_readlane_b32 s42, v252, 43
	v_readlane_b32 s43, v252, 44
	v_readlane_b32 s44, v252, 45
	v_readlane_b32 s45, v252, 46
	v_readlane_b32 s46, v252, 47
	v_readlane_b32 s47, v252, 48
	v_readlane_b32 s48, v252, 49
	v_readlane_b32 s49, v252, 50
	v_readlane_b32 s50, v252, 51
	v_readlane_b32 s51, v252, 52
	s_waitcnt vmcnt(1)
	v_xor_b32_e32 v117, 0x80000000, v48
	v_cmp_ngt_f32_e32 vcc, s0, v48
	s_and_saveexec_b64 s[0:1], vcc
	s_cbranch_execz .LBB0_406
; DI float softplus_f(float x) { return x > 20.f ? x : log1pf(__expf(x)); }
; PH void lru_item(const Params& p, int layer, int b, int n, int dpart) {
;     ...
;   const float cl = -8.f * softplus_f(-p.in[17][layer * 768 + chg]);
	v_mul_f32_e32 v48, 0xbfb8aa3b, v48
	v_exp_f32_e32 v62, v48
	s_mov_b32 s7, 0x3f2aaaab
	v_add_f32_e32 v50, 1.0, v62
	v_frexp_mant_f32_e32 v52, v50
	v_cvt_f64_f32_e32 v[48:49], v50
	v_frexp_exp_i32_f64_e32 v48, v[48:49]
	v_cmp_gt_f32_e32 vcc, s7, v52
	v_add_f32_e32 v51, -1.0, v50
	v_sub_f32_e32 v53, v51, v50
	v_subbrev_co_u32_e32 v56, vcc, 0, v48, vcc
	v_sub_u32_e32 v48, 0, v56
	v_sub_f32_e32 v51, v62, v51
	v_add_f32_e32 v53, 1.0, v53
	v_ldexp_f32 v49, v50, v48
	v_add_f32_e32 v51, v51, v53
	v_add_f32_e32 v50, -1.0, v49
	v_add_f32_e32 v52, 1.0, v49
	v_ldexp_f32 v48, v51, v48
	v_add_f32_e32 v51, 1.0, v50
	v_add_f32_e32 v53, -1.0, v52
	v_sub_f32_e32 v51, v49, v51
	v_sub_f32_e32 v49, v49, v53
	v_add_f32_e32 v51, v48, v51
	v_add_f32_e32 v48, v48, v49
	v_add_f32_e32 v57, v52, v48
	v_rcp_f32_e32 v59, v57
	v_sub_f32_e32 v49, v57, v52
	v_sub_f32_e32 v58, v48, v49
	v_add_f32_e32 v49, v50, v51
	v_mul_f32_e32 v61, v49, v59
	v_sub_f32_e32 v48, v49, v50
	v_mul_f32_e32 v50, v57, v61
	v_fma_f32 v52, v61, v57, -v50
	v_fmac_f32_e32 v52, v61, v58
	v_sub_f32_e32 v60, v51, v48
	v_add_f32_e32 v48, v50, v52
	v_sub_f32_e32 v51, v49, v48
	v_pk_add_f32 v[54:55], v[48:49], v[50:51] neg_lo:[0,1] neg_hi:[0,1]
	v_mov_b32_e32 v53, v48
	v_pk_add_f32 v[48:49], v[54:55], v[52:53] neg_lo:[0,1] neg_hi:[0,1]
	s_mov_b32 s7, 0x3f317218
	v_add_f32_e32 v49, v60, v49
	v_add_f32_e32 v48, v48, v49
	v_add_f32_e32 v49, v51, v48
	v_mul_f32_e32 v60, v59, v49
	v_mul_f32_e32 v50, v57, v60
	v_fma_f32 v52, v60, v57, -v50
	v_fmac_f32_e32 v52, v60, v58
	v_sub_f32_e32 v51, v51, v49
	v_add_f32_e32 v57, v48, v51
	v_add_f32_e32 v48, v50, v52
	v_sub_f32_e32 v51, v49, v48
	v_pk_add_f32 v[54:55], v[48:49], v[50:51] neg_lo:[0,1] neg_hi:[0,1]
	v_mov_b32_e32 v53, v48
	v_pk_add_f32 v[48:49], v[54:55], v[52:53] neg_lo:[0,1] neg_hi:[0,1]
	s_nop 0
	v_add_f32_e32 v49, v57, v49
	v_add_f32_e32 v48, v48, v49
	v_add_f32_e32 v49, v61, v60
	v_add_f32_e32 v48, v51, v48
	v_sub_f32_e32 v50, v49, v61
	v_mul_f32_e32 v48, v59, v48
	v_sub_f32_e32 v50, v60, v50
	v_add_f32_e32 v50, v50, v48
	v_add_f32_e32 v52, v49, v50
	v_mul_f32_e32 v53, v52, v52
	v_fmamk_f32 v48, v53, 0x3e9b6dac, v184
	v_fmaak_f32 v163, v53, v48, 0x3f2aaada
	v_cvt_f32_i32_e32 v48, v56
	v_sub_f32_e32 v49, v52, v49
	v_sub_f32_e32 v49, v50, v49
	v_ldexp_f32 v54, v49, 1
	v_mul_f32_e32 v49, v52, v53
	v_ldexp_f32 v51, v52, 1
	v_pk_mul_f32 v[52:53], v[48:49], v[162:163]
	s_nop 0
	v_fma_f32 v50, v48, s7, -v52
	v_fmac_f32_e32 v50, 0xb102e308, v48
	v_pk_add_f32 v[48:49], v[52:53], v[50:51]
	s_mov_b32 s7, 0x7f800000
	v_sub_f32_e32 v51, v49, v51
	v_sub_f32_e32 v51, v53, v51
	v_add_f32_e32 v55, v54, v51
	v_mov_b32_e32 v54, v52
	v_pk_add_f32 v[52:53], v[48:49], v[52:53] neg_lo:[0,1] neg_hi:[0,1]
	v_pk_add_f32 v[56:57], v[48:49], v[54:55]
	v_mov_b32_e32 v51, v48
	v_mov_b32_e32 v53, v57
	v_pk_add_f32 v[58:59], v[50:51], v[52:53] neg_lo:[0,1] neg_hi:[0,1]
	v_pk_add_f32 v[50:51], v[50:51], v[52:53]
	v_mov_b32_e32 v54, v55
	v_pk_add_f32 v[52:53], v[50:51], v[48:49] op_sel:[1,0] op_sel_hi:[0,1] neg_lo:[0,1] neg_hi:[0,1]
	v_pk_add_f32 v[60:61], v[56:57], v[52:53] op_sel_hi:[1,0] neg_lo:[0,1] neg_hi:[0,1]
	v_mov_b32_e32 v56, v57
	v_mov_b32_e32 v57, v51
	v_pk_mov_b32 v[52:53], v[48:49], v[52:53] op_sel:[1,0]
	v_mov_b32_e32 v55, v48
	v_pk_add_f32 v[52:53], v[56:57], v[52:53] neg_lo:[0,1] neg_hi:[0,1]
	v_mov_b32_e32 v60, v58
	v_pk_add_f32 v[48:49], v[54:55], v[52:53] neg_lo:[0,1] neg_hi:[0,1]
	v_mov_b32_e32 v59, v51
	v_pk_add_f32 v[52:53], v[60:61], v[48:49]
	v_cmp_neq_f32_e32 vcc, s7, v62
	v_pk_add_f32 v[54:55], v[52:53], v[52:53] op_sel:[0,1] op_sel_hi:[1,0]
	s_mov_b32 s7, 0x33800000
	v_pk_add_f32 v[50:51], v[50:51], v[54:55] op_sel:[1,0] op_sel_hi:[0,1]
	v_mov_b32_e32 v53, v50
	v_pk_add_f32 v[56:57], v[52:53], v[58:59] neg_lo:[0,1] neg_hi:[0,1]
	v_mov_b32_e32 v49, v54
	v_sub_f32_e32 v51, v52, v56
	v_pk_add_f32 v[48:49], v[48:49], v[56:57] neg_lo:[0,1] neg_hi:[0,1]
	v_sub_f32_e32 v51, v58, v51
	v_add_f32_e32 v48, v48, v51
	v_add_f32_e32 v48, v48, v49
	v_add_f32_e32 v48, v50, v48
	v_cndmask_b32_e32 v48, v196, v48, vcc
	v_cmp_ngt_f32_e32 vcc, -1.0, v62
	s_nop 1
	v_cndmask_b32_e32 v48, v197, v48, vcc
	v_cmp_neq_f32_e32 vcc, -1.0, v62
	s_nop 1
	v_cndmask_b32_e32 v48, v191, v48, vcc
	v_cmp_lt_f32_e64 vcc, |v62|, s7
	s_nop 1
	v_cndmask_b32_e32 v117, v48, v62, vcc
